# v14
# speedup vs baseline: 1.0523x; 1.0189x over previous
.LBB0_176:
	s_add_i32 s8, s81, 0xffffff81
	v_cmp_le_i32_e32 vcc, s8, v141
	s_and_b64 s[8:9], s[12:13], vcc
	s_and_saveexec_b64 s[16:17], s[8:9]
	s_cbranch_execz .LBB0_180
	v_add_u32_e32 v1, v145, v143
	ds_read_b128 v[66:69], v142
	ds_read_b128 v[70:73], v142 offset:64
	ds_read_b128 v[74:77], v142 offset:128
	ds_read_b128 v[78:81], v142 offset:192
	v_add_u32_e32 v186, v145, v143
	ds_read_b128 v[154:157], v186 offset:8704
	ds_read_b128 v[158:161], v186 offset:10752
	ds_read_b128 v[162:165], v186 offset:12800
	ds_read_b128 v[166:169], v186 offset:14848
	v_add_u32_e32 v187, v147, v143
	ds_read_b128 v[170:173], v187 offset:8704
	ds_read_b128 v[174:177], v187 offset:10752
	ds_read_b128 v[178:181], v187 offset:12800
	ds_read_b128 v[182:185], v187 offset:14848
	s_sub_i32 s8, s81, 64
	v_cmp_gt_i32_e32 vcc, s8, v136
	s_waitcnt lgkmcnt(7)
	v_mfma_f32_16x16x32_bf16 v[86:89], v[154:157], v[30:33], v[66:69]
	s_nop 0
	v_mfma_f32_16x16x32_bf16 v[66:69], v[154:157], v[26:29], v[66:69]
	s_waitcnt lgkmcnt(6)
	v_mfma_f32_16x16x32_bf16 v[90:93], v[158:161], v[30:33], v[70:73]
	v_mfma_f32_16x16x32_bf16 v[70:73], v[158:161], v[26:29], v[70:73]
	s_waitcnt lgkmcnt(5)
	v_mfma_f32_16x16x32_bf16 v[94:97], v[162:165], v[30:33], v[74:77]
	v_mfma_f32_16x16x32_bf16 v[112:115], v[162:165], v[26:29], v[74:77]
	v_add_u32_e32 v1, v147, v143
	s_waitcnt lgkmcnt(4)
	v_mfma_f32_16x16x32_bf16 v[116:119], v[166:169], v[30:33], v[78:81]
	v_mfma_f32_16x16x32_bf16 v[120:123], v[166:169], v[26:29], v[78:81]
	s_waitcnt lgkmcnt(3)
	v_mfma_f32_16x16x32_bf16 v[82:85], v[170:173], v[18:21], v[66:69]
	v_mfma_f32_16x16x32_bf16 v[74:77], v[170:173], v[22:25], v[86:89]
	s_waitcnt lgkmcnt(2)
	v_mfma_f32_16x16x32_bf16 v[90:93], v[174:177], v[22:25], v[90:93]
	v_mfma_f32_16x16x32_bf16 v[86:89], v[174:177], v[18:21], v[70:73]
	s_waitcnt lgkmcnt(1)
	v_mfma_f32_16x16x32_bf16 v[78:81], v[178:181], v[22:25], v[94:97]
	v_mfma_f32_16x16x32_bf16 v[66:69], v[178:181], v[18:21], v[112:115]
	s_waitcnt lgkmcnt(0)
	v_mfma_f32_16x16x32_bf16 v[94:97], v[182:185], v[22:25], v[116:119]
	v_mfma_f32_16x16x32_bf16 v[70:73], v[182:185], v[18:21], v[120:123]
	s_and_saveexec_b64 s[78:79], vcc
	s_cbranch_execz .LBB0_179
	v_add_u32_e32 v1, s81, v137
	v_add_u32_e32 v113, 0xffffff81, v1
	v_mov_b32_e32 v112, s41
	v_cmp_gt_i32_e32 vcc, v113, v148
	v_cmp_lt_i32_e64 s[8:9], v113, v148
	v_add_u32_e32 v114, 0xffffff83, v1
	v_cndmask_b32_e32 v112, v74, v112, vcc
	v_cndmask_b32_e64 v74, v112, v74, s[8:9]
	v_cndmask_b32_e64 v75, v221, v75, s[8:9]
	v_cmp_le_i32_e64 s[8:9], v114, v148
	v_add_u32_e32 v115, 0xffffff84, v1
	v_mov_b32_e32 v112, s41
	v_cndmask_b32_e64 v76, v221, v76, s[8:9]
	v_cmp_le_i32_e64 s[8:9], v115, v148
	v_add_u32_e32 v116, 0xffffffa4, v1
	s_nop 0
	v_cndmask_b32_e64 v77, v221, v77, s[8:9]
	v_cmp_gt_i32_e64 s[8:9], v113, v149
	s_nop 1
	v_cndmask_b32_e64 v112, v82, v112, s[8:9]
	v_cmp_lt_i32_e64 s[8:9], v113, v149
	v_add_u32_e32 v113, 0xffffff91, v1
	s_nop 0
	v_cndmask_b32_e64 v82, v112, v82, s[8:9]
	v_cndmask_b32_e64 v83, v221, v83, s[8:9]
	v_cmp_le_i32_e64 s[8:9], v114, v149
	v_mov_b32_e32 v112, s41
	v_add_u32_e32 v114, 0xffffff93, v1
	v_cndmask_b32_e64 v84, v221, v84, s[8:9]
	v_cmp_le_i32_e64 s[8:9], v115, v149
	v_cndmask_b32_e32 v86, v86, v112, vcc
	v_add_u32_e32 v115, 0xffffff94, v1
	v_cndmask_b32_e64 v85, v221, v85, s[8:9]
	v_cmp_gt_i32_e64 s[8:9], v113, v148
	v_add_u32_e32 v113, 0xffffff92, v1
	v_cmp_le_i32_e32 vcc, v113, v149
	v_cndmask_b32_e64 v90, v90, v112, s[8:9]
	v_cmp_le_i32_e64 s[8:9], v113, v148
	v_cndmask_b32_e32 v87, v221, v87, vcc
	v_cmp_le_i32_e32 vcc, v114, v149
	v_add_u32_e32 v113, 0xffffffa1, v1
	v_cndmask_b32_e64 v91, v221, v91, s[8:9]
	v_cndmask_b32_e32 v88, v221, v88, vcc
	v_cmp_le_i32_e32 vcc, v115, v149
	v_cmp_le_i32_e64 s[8:9], v114, v148
	v_add_u32_e32 v114, 0xffffffa2, v1
	v_cndmask_b32_e32 v89, v221, v89, vcc
	v_cmp_gt_i32_e32 vcc, v113, v148
	v_cndmask_b32_e64 v92, v221, v92, s[8:9]
	v_cmp_le_i32_e64 s[8:9], v115, v148
	v_cndmask_b32_e32 v78, v78, v112, vcc
	v_cmp_le_i32_e32 vcc, v114, v148
	v_add_u32_e32 v115, 0xffffffa3, v1
	v_cndmask_b32_e64 v93, v221, v93, s[8:9]
	v_cndmask_b32_e32 v79, v221, v79, vcc
	v_cmp_le_i32_e32 vcc, v115, v148
	s_nop 1
	v_cndmask_b32_e32 v80, v221, v80, vcc
	v_cmp_le_i32_e32 vcc, v116, v148
	s_nop 1
	v_cndmask_b32_e32 v81, v221, v81, vcc
	v_cmp_gt_i32_e32 vcc, v113, v149
	v_add_u32_e32 v113, 0xffffffb1, v1
	s_nop 0
	v_cndmask_b32_e32 v66, v66, v112, vcc
	v_cmp_le_i32_e32 vcc, v114, v149
	v_add_u32_e32 v114, 0xffffffb2, v1
	s_nop 0
	v_cndmask_b32_e32 v67, v221, v67, vcc
	v_cmp_le_i32_e32 vcc, v115, v149
	v_add_u32_e32 v115, 0xffffffb3, v1
	v_add_u32_e32 v1, 0xffffffb4, v1
	v_cndmask_b32_e32 v68, v221, v68, vcc
	v_cmp_le_i32_e32 vcc, v116, v149
	s_nop 1
	v_cndmask_b32_e32 v69, v221, v69, vcc
	v_cmp_gt_i32_e32 vcc, v113, v148
	s_nop 1
	v_cndmask_b32_e32 v94, v94, v112, vcc
	v_cmp_le_i32_e32 vcc, v114, v148
	s_nop 1
	v_cndmask_b32_e32 v95, v221, v95, vcc
	v_cmp_le_i32_e32 vcc, v115, v148
	s_nop 1
	v_cndmask_b32_e32 v96, v221, v96, vcc
	v_cmp_le_i32_e32 vcc, v1, v148
	s_nop 1
	v_cndmask_b32_e32 v97, v221, v97, vcc
	v_cmp_gt_i32_e32 vcc, v113, v149
	s_nop 1
	v_cndmask_b32_e32 v70, v70, v112, vcc
	v_cmp_le_i32_e32 vcc, v114, v149
	s_nop 1
	v_cndmask_b32_e32 v71, v221, v71, vcc
	v_cmp_le_i32_e32 vcc, v115, v149
	s_nop 1
	v_cndmask_b32_e32 v72, v221, v72, vcc
	v_cmp_le_i32_e32 vcc, v1, v149
	s_nop 1
	v_cndmask_b32_e32 v73, v221, v73, vcc
.LBB0_179:
	s_or_b64 exec, exec, s[78:79]
	v_max_f32_e32 v1, v77, v77
	v_max_f32_e32 v112, v76, v76
	v_max_f32_e32 v1, v112, v1
	v_max_f32_e32 v112, v93, v93
	v_max_f32_e32 v113, v92, v92
	v_max_f32_e32 v112, v113, v112
	v_max3_f32 v1, v74, v75, v1
	v_max3_f32 v112, v90, v91, v112
	v_max3_f32 v1, v1, s41, v112
	v_max_f32_e32 v112, v81, v81
	v_max_f32_e32 v113, v80, v80
	v_max_f32_e32 v112, v113, v112
	v_max_f32_e32 v113, v97, v97
	v_max_f32_e32 v114, v96, v96
	v_max_f32_e32 v113, v114, v113
	v_max3_f32 v112, v78, v79, v112
	v_max3_f32 v113, v94, v95, v113
	v_max3_f32 v1, v1, v112, v113
	ds_bpermute_b32 v112, v135, v1
	s_waitcnt lgkmcnt(0)
	v_max_f32_e32 v112, v112, v112
	v_max_f32_e32 v1, v1, v112
	ds_bpermute_b32 v112, v101, v1
	s_waitcnt lgkmcnt(0)
	v_max3_f32 v1, v111, v1, v112
	v_sub_f32_e32 v74, v74, v1
	v_sub_f32_e32 v112, v111, v1
	v_exp_f32_e32 v111, v74
	v_sub_f32_e32 v74, v75, v1
	v_exp_f32_e32 v113, v74
	v_sub_f32_e32 v74, v76, v1
	v_exp_f32_e32 v115, v74
	v_sub_f32_e32 v74, v77, v1
	v_exp_f32_e32 v117, v74
	v_sub_f32_e32 v74, v90, v1
	v_exp_f32_e32 v119, v74
	v_sub_f32_e32 v74, v91, v1
	v_exp_f32_e32 v91, v74
	v_sub_f32_e32 v74, v92, v1
	v_exp_f32_e32 v121, v74
	v_sub_f32_e32 v74, v93, v1
	v_exp_f32_e32 v93, v74
	v_sub_f32_e32 v74, v78, v1
	v_exp_f32_e32 v123, v74
	v_sub_f32_e32 v74, v79, v1
	v_exp_f32_e32 v125, v74
	v_sub_f32_e32 v74, v80, v1
	v_exp_f32_e32 v127, v74
	v_sub_f32_e32 v74, v81, v1
	v_max_f32_e32 v90, v85, v85
	v_max_f32_e32 v92, v84, v84
	v_exp_f32_e32 v129, v74
	v_sub_f32_e32 v74, v94, v1
	v_max_f32_e32 v90, v92, v90
	v_max_f32_e32 v92, v89, v89
	v_max_f32_e32 v94, v88, v88
	v_max_f32_e32 v92, v94, v92
	v_max3_f32 v90, v82, v83, v90
	v_max3_f32 v92, v86, v87, v92
	v_exp_f32_e32 v131, v74
	v_sub_f32_e32 v74, v95, v1
	v_max3_f32 v90, v90, s41, v92
	v_max_f32_e32 v92, v69, v69
	v_max_f32_e32 v94, v68, v68
	v_exp_f32_e32 v95, v74
	v_sub_f32_e32 v74, v96, v1
	v_max_f32_e32 v92, v94, v92
	v_max_f32_e32 v94, v73, v73
	v_max_f32_e32 v96, v72, v72
	v_max_f32_e32 v94, v96, v94
	v_max3_f32 v92, v66, v67, v92
	v_max3_f32 v94, v70, v71, v94
	v_max3_f32 v90, v90, v92, v94
	ds_bpermute_b32 v92, v135, v90
	v_exp_f32_e32 v134, v112
	v_exp_f32_e32 v133, v74
	v_sub_f32_e32 v74, v97, v1
	v_exp_f32_e32 v97, v74
	s_waitcnt lgkmcnt(0)
	v_max_f32_e32 v92, v92, v92
	v_max_f32_e32 v90, v90, v92
	ds_bpermute_b32 v92, v101, v90
	v_pk_mul_f32 v[80:81], v[52:53], v[134:135] op_sel_hi:[1,0]
	v_pk_mul_f32 v[78:79], v[50:51], v[134:135] op_sel_hi:[1,0]
	v_pk_mul_f32 v[76:77], v[56:57], v[134:135] op_sel_hi:[1,0]
	v_pk_mul_f32 v[74:75], v[54:55], v[134:135] op_sel_hi:[1,0]
	s_waitcnt lgkmcnt(0)
	v_max3_f32 v151, v110, v90, v92
	v_sub_f32_e32 v82, v82, v151
	v_sub_f32_e32 v152, v110, v151
	v_exp_f32_e32 v110, v82
	v_sub_f32_e32 v82, v83, v151
	v_exp_f32_e32 v112, v82
	v_sub_f32_e32 v82, v84, v151
	v_exp_f32_e32 v114, v82
	v_sub_f32_e32 v82, v85, v151
	v_sub_f32_e32 v66, v66, v151
	v_exp_f32_e32 v116, v82
	v_sub_f32_e32 v82, v86, v151
	v_exp_f32_e32 v122, v66
	v_sub_f32_e32 v66, v67, v151
	v_exp_f32_e32 v118, v82
	v_sub_f32_e32 v82, v87, v151
	v_exp_f32_e32 v124, v66
	v_pk_add_f32 v[66:67], v[110:111], 0 op_sel_hi:[1,0]
	v_exp_f32_e32 v90, v82
	v_sub_f32_e32 v82, v88, v151
	v_pk_add_f32 v[66:67], v[112:113], v[66:67]
	v_exp_f32_e32 v120, v82
	v_sub_f32_e32 v82, v89, v151
	v_pk_add_f32 v[66:67], v[114:115], v[66:67]
	v_exp_f32_e32 v92, v82
	v_pk_add_f32 v[66:67], v[116:117], v[66:67]
	v_sub_f32_e32 v68, v68, v151
	v_pk_add_f32 v[66:67], v[118:119], v[66:67]
	v_exp_f32_e32 v126, v68
	v_pk_add_f32 v[66:67], v[90:91], v[66:67]
	v_sub_f32_e32 v68, v69, v151
	v_pk_add_f32 v[66:67], v[120:121], v[66:67]
	v_exp_f32_e32 v128, v68
	v_pk_add_f32 v[66:67], v[92:93], v[66:67]
	v_sub_f32_e32 v68, v70, v151
	v_pk_add_f32 v[66:67], v[122:123], v[66:67]
	v_exp_f32_e32 v130, v68
	v_sub_f32_e32 v68, v71, v151
	v_pk_add_f32 v[66:67], v[124:125], v[66:67]
	v_exp_f32_e32 v94, v68
	v_sub_f32_e32 v68, v72, v151
	v_exp_f32_e32 v132, v68
	v_sub_f32_e32 v68, v73, v151
	v_pk_add_f32 v[66:67], v[126:127], v[66:67]
	v_exp_f32_e32 v96, v68
	v_pk_add_f32 v[66:67], v[128:129], v[66:67]
	v_exp_f32_e32 v82, v152
	v_pk_add_f32 v[66:67], v[130:131], v[66:67]
	v_mov_b32_e32 v83, v134
	v_pk_add_f32 v[66:67], v[94:95], v[66:67]
	v_add_u32_e32 v86, v150, v144
	v_pk_add_f32 v[66:67], v[132:133], v[66:67]
	v_pk_mul_f32 v[68:69], v[36:37], v[82:83] op_sel_hi:[1,0]
	v_pk_add_f32 v[66:67], v[96:97], v[66:67]
	v_pk_mul_f32 v[72:73], v[40:41], v[82:83] op_sel_hi:[1,0]
	v_pk_fma_f32 v[104:105], v[104:105], v[82:83], v[66:67]
	v_pk_mul_f32 v[66:67], v[34:35], v[82:83] op_sel_hi:[1,0]
	v_pk_mul_f32 v[70:71], v[38:39], v[82:83] op_sel_hi:[1,0]
	v_pk_mul_f32 v[44:45], v[44:45], v[82:83] op_sel_hi:[1,0]
	v_pk_mul_f32 v[42:43], v[42:43], v[82:83] op_sel_hi:[1,0]
	v_pk_mul_f32 v[36:37], v[48:49], v[82:83] op_sel_hi:[1,0]
	v_pk_mul_f32 v[34:35], v[46:47], v[82:83] op_sel_hi:[1,0]
	v_add_u32_e32 v186, v150, v144
	ds_read_b128 v[154:157], v186 offset:25088
	ds_read_b128 v[158:161], v186 offset:27136
	ds_read_b128 v[162:165], v186 offset:29184
	ds_read_b128 v[166:169], v186 offset:31232
	v_add_u32_e32 v187, v150, v146
	ds_read_b128 v[170:173], v187 offset:27136
	ds_read_b128 v[174:177], v187 offset:25088
	ds_read_b128 v[178:181], v187 offset:29184
	ds_read_b128 v[182:185], v187 offset:31232
	v_cvt_pk_bf16_f32 v54, v111, v113
	v_cvt_pk_bf16_f32 v55, v115, v117
	v_cvt_pk_bf16_f32 v56, v119, v91
	v_cvt_pk_bf16_f32 v57, v121, v93
	v_cvt_pk_bf16_f32 v38, v110, v112
	v_cvt_pk_bf16_f32 v39, v114, v116
	v_cvt_pk_bf16_f32 v40, v118, v90
	v_cvt_pk_bf16_f32 v41, v120, v92
	v_pk_mul_f32 v[60:61], v[60:61], v[134:135] op_sel_hi:[1,0]
	s_waitcnt lgkmcnt(7)
	v_mfma_f32_16x16x32_bf16 v[78:81], v[154:157], v[54:57], v[78:81]
	v_mul_f32_e64 v58, v58, v134
	v_mul_f32_e64 v59, v59, v134
	v_pk_mul_f32 v[52:53], v[64:65], v[134:135] op_sel_hi:[1,0]
	v_pk_mul_f32 v[50:51], v[62:63], v[134:135] op_sel_hi:[1,0]
	v_mfma_f32_16x16x32_bf16 v[66:69], v[154:157], v[38:41], v[66:69]
	v_add_u32_e32 v90, v150, v146
	v_cvt_pk_bf16_f32 v62, v123, v125
	s_waitcnt lgkmcnt(6)
	v_mfma_f32_16x16x32_bf16 v[74:77], v[158:161], v[54:57], v[74:77]
	v_cvt_pk_bf16_f32 v63, v127, v129
	v_cvt_pk_bf16_f32 v64, v131, v95
	v_cvt_pk_bf16_f32 v65, v133, v97
	v_mfma_f32_16x16x32_bf16 v[70:73], v[158:161], v[38:41], v[70:73]
	v_cvt_pk_bf16_f32 v46, v122, v124
	v_cvt_pk_bf16_f32 v47, v126, v128
	s_waitcnt lgkmcnt(5)
	v_mfma_f32_16x16x32_bf16 v[58:61], v[162:165], v[54:57], v[58:61]
	v_cvt_pk_bf16_f32 v48, v130, v94
	v_cvt_pk_bf16_f32 v49, v132, v96
	v_mov_b32_e32 v110, v151
	v_mfma_f32_16x16x32_bf16 v[42:45], v[162:165], v[38:41], v[42:45]
	v_mov_b32_e32 v111, v1
	s_waitcnt lgkmcnt(4)
	v_mfma_f32_16x16x32_bf16 v[86:89], v[166:169], v[54:57], v[50:53]
	v_mfma_f32_16x16x32_bf16 v[82:85], v[166:169], v[38:41], v[34:37]
	s_waitcnt lgkmcnt(2)
	v_mfma_f32_16x16x32_bf16 v[50:53], v[174:177], v[62:65], v[78:81]
	v_mfma_f32_16x16x32_bf16 v[34:37], v[174:177], v[46:49], v[66:69]
	s_waitcnt lgkmcnt(1)
	v_mfma_f32_16x16x32_bf16 v[58:61], v[178:181], v[62:65], v[58:61]
	v_mfma_f32_16x16x32_bf16 v[42:45], v[178:181], v[46:49], v[42:45]
	v_mfma_f32_16x16x32_bf16 v[54:57], v[170:173], v[62:65], v[74:77]
	v_mfma_f32_16x16x32_bf16 v[38:41], v[170:173], v[46:49], v[70:73]
	s_waitcnt lgkmcnt(0)
	v_mfma_f32_16x16x32_bf16 v[62:65], v[182:185], v[62:65], v[86:89]
	v_mfma_f32_16x16x32_bf16 v[46:49], v[182:185], v[46:49], v[82:85]

.LBB0_185:
	s_sub_i32 s8, s81, 63
	v_cmp_le_i32_e32 vcc, s8, v141
	s_and_b64 s[8:9], s[12:13], vcc
	s_and_saveexec_b64 s[16:17], s[8:9]
	s_cbranch_execz .LBB0_189
	v_add_u32_e32 v1, v145, v143
	ds_read_b128 v[66:69], v142 offset:256
	ds_read_b128 v[70:73], v142 offset:320
	ds_read_b128 v[74:77], v142 offset:384
	ds_read_b128 v[78:81], v142 offset:448
	v_add_u32_e32 v186, v145, v143
	ds_read_b128 v[154:157], v186 offset:16896
	ds_read_b128 v[158:161], v186 offset:18944
	ds_read_b128 v[162:165], v186 offset:20992
	ds_read_b128 v[166:169], v186 offset:23040
	v_add_u32_e32 v187, v147, v143
	ds_read_b128 v[170:173], v187 offset:16896
	ds_read_b128 v[174:177], v187 offset:18944
	ds_read_b128 v[178:181], v187 offset:20992
	ds_read_b128 v[182:185], v187 offset:23040
	v_cmp_gt_i32_e32 vcc, s81, v136
	s_waitcnt lgkmcnt(7)
	v_mfma_f32_16x16x32_bf16 v[86:89], v[154:157], v[30:33], v[66:69]
	s_nop 0
	v_mfma_f32_16x16x32_bf16 v[82:85], v[154:157], v[26:29], v[66:69]
	s_waitcnt lgkmcnt(6)
	v_mfma_f32_16x16x32_bf16 v[90:93], v[158:161], v[30:33], v[70:73]
	v_mfma_f32_16x16x32_bf16 v[70:73], v[158:161], v[26:29], v[70:73]
	s_waitcnt lgkmcnt(5)
	v_mfma_f32_16x16x32_bf16 v[94:97], v[162:165], v[30:33], v[74:77]
	v_mfma_f32_16x16x32_bf16 v[112:115], v[162:165], v[26:29], v[74:77]
	v_add_u32_e32 v1, v147, v143
	s_waitcnt lgkmcnt(4)
	v_mfma_f32_16x16x32_bf16 v[116:119], v[166:169], v[30:33], v[78:81]
	v_mfma_f32_16x16x32_bf16 v[78:81], v[166:169], v[26:29], v[78:81]
	s_waitcnt lgkmcnt(3)
	v_mfma_f32_16x16x32_bf16 v[66:69], v[170:173], v[22:25], v[86:89]
	s_nop 0
	v_mfma_f32_16x16x32_bf16 v[86:89], v[170:173], v[18:21], v[82:85]
	s_waitcnt lgkmcnt(2)
	v_mfma_f32_16x16x32_bf16 v[90:93], v[174:177], v[22:25], v[90:93]
	v_mfma_f32_16x16x32_bf16 v[74:77], v[174:177], v[18:21], v[70:73]
	s_waitcnt lgkmcnt(1)
	v_mfma_f32_16x16x32_bf16 v[82:85], v[178:181], v[22:25], v[94:97]
	v_mfma_f32_16x16x32_bf16 v[70:73], v[178:181], v[18:21], v[112:115]
	s_waitcnt lgkmcnt(0)
	v_mfma_f32_16x16x32_bf16 v[94:97], v[182:185], v[22:25], v[116:119]
	v_mfma_f32_16x16x32_bf16 v[78:81], v[182:185], v[18:21], v[78:81]
	s_and_saveexec_b64 s[78:79], vcc
	s_cbranch_execz .LBB0_188
	v_add_u32_e32 v1, s81, v137
	v_subrev_u32_e32 v113, 63, v1
	v_mov_b32_e32 v112, s41
	v_cmp_gt_i32_e32 vcc, v113, v148
	v_cmp_lt_i32_e64 s[8:9], v113, v148
	v_subrev_u32_e32 v114, 61, v1
	v_cndmask_b32_e32 v112, v66, v112, vcc
	v_cndmask_b32_e64 v66, v112, v66, s[8:9]
	v_cndmask_b32_e64 v67, v221, v67, s[8:9]
	v_cmp_le_i32_e64 s[8:9], v114, v148
	v_subrev_u32_e32 v115, 60, v1
	v_mov_b32_e32 v112, s41
	v_cndmask_b32_e64 v68, v221, v68, s[8:9]
	v_cmp_le_i32_e64 s[8:9], v115, v148
	v_subrev_u32_e32 v116, 28, v1
	s_nop 0
	v_cndmask_b32_e64 v69, v221, v69, s[8:9]
	v_cmp_gt_i32_e64 s[8:9], v113, v149
	s_nop 1
	v_cndmask_b32_e64 v112, v86, v112, s[8:9]
	v_cmp_lt_i32_e64 s[8:9], v113, v149
	v_subrev_u32_e32 v113, 47, v1
	s_nop 0
	v_cndmask_b32_e64 v86, v112, v86, s[8:9]
	v_cndmask_b32_e64 v87, v221, v87, s[8:9]
	v_cmp_le_i32_e64 s[8:9], v114, v149
	v_mov_b32_e32 v112, s41
	v_subrev_u32_e32 v114, 45, v1
	v_cndmask_b32_e64 v88, v221, v88, s[8:9]
	v_cmp_le_i32_e64 s[8:9], v115, v149
	v_cndmask_b32_e32 v74, v74, v112, vcc
	v_subrev_u32_e32 v115, 44, v1
	v_cndmask_b32_e64 v89, v221, v89, s[8:9]
	v_cmp_gt_i32_e64 s[8:9], v113, v148
	v_subrev_u32_e32 v113, 46, v1
	v_cmp_le_i32_e32 vcc, v113, v149
	v_cndmask_b32_e64 v90, v90, v112, s[8:9]
	v_cmp_le_i32_e64 s[8:9], v113, v148
	v_cndmask_b32_e32 v75, v221, v75, vcc
	v_cmp_le_i32_e32 vcc, v114, v149
	v_subrev_u32_e32 v113, 31, v1
	v_cndmask_b32_e64 v91, v221, v91, s[8:9]
	v_cndmask_b32_e32 v76, v221, v76, vcc
	v_cmp_le_i32_e32 vcc, v115, v149
	v_cmp_le_i32_e64 s[8:9], v114, v148
	v_subrev_u32_e32 v114, 30, v1
	v_cndmask_b32_e32 v77, v221, v77, vcc
	v_cmp_gt_i32_e32 vcc, v113, v148
	v_cndmask_b32_e64 v92, v221, v92, s[8:9]
	v_cmp_le_i32_e64 s[8:9], v115, v148
	v_cndmask_b32_e32 v82, v82, v112, vcc
	v_cmp_le_i32_e32 vcc, v114, v148
	v_subrev_u32_e32 v115, 29, v1
	v_cndmask_b32_e64 v93, v221, v93, s[8:9]
	v_cndmask_b32_e32 v83, v221, v83, vcc
	v_cmp_le_i32_e32 vcc, v115, v148
	s_nop 1
	v_cndmask_b32_e32 v84, v221, v84, vcc
	v_cmp_le_i32_e32 vcc, v116, v148
	s_nop 1
	v_cndmask_b32_e32 v85, v221, v85, vcc
	v_cmp_gt_i32_e32 vcc, v113, v149
	v_add_u32_e32 v113, -15, v1
	s_nop 0
	v_cndmask_b32_e32 v70, v70, v112, vcc
	v_cmp_le_i32_e32 vcc, v114, v149
	v_add_u32_e32 v114, -14, v1
	s_nop 0
	v_cndmask_b32_e32 v71, v221, v71, vcc
	v_cmp_le_i32_e32 vcc, v115, v149
	v_add_u32_e32 v115, -13, v1
	v_add_u32_e32 v1, -12, v1
	v_cndmask_b32_e32 v72, v221, v72, vcc
	v_cmp_le_i32_e32 vcc, v116, v149
	s_nop 1
	v_cndmask_b32_e32 v73, v221, v73, vcc
	v_cmp_gt_i32_e32 vcc, v113, v148
	s_nop 1
	v_cndmask_b32_e32 v94, v94, v112, vcc
	v_cmp_le_i32_e32 vcc, v114, v148
	s_nop 1
	v_cndmask_b32_e32 v95, v221, v95, vcc
	v_cmp_le_i32_e32 vcc, v115, v148
	s_nop 1
	v_cndmask_b32_e32 v96, v221, v96, vcc
	v_cmp_le_i32_e32 vcc, v1, v148
	s_nop 1
	v_cndmask_b32_e32 v97, v221, v97, vcc
	v_cmp_gt_i32_e32 vcc, v113, v149
	s_nop 1
	v_cndmask_b32_e32 v78, v78, v112, vcc
	v_cmp_le_i32_e32 vcc, v114, v149
	s_nop 1
	v_cndmask_b32_e32 v79, v221, v79, vcc
	v_cmp_le_i32_e32 vcc, v115, v149
	s_nop 1
	v_cndmask_b32_e32 v80, v221, v80, vcc
	v_cmp_le_i32_e32 vcc, v1, v149
	s_nop 1
	v_cndmask_b32_e32 v81, v221, v81, vcc
.LBB0_188:
	s_or_b64 exec, exec, s[78:79]
	v_max_f32_e32 v1, v69, v69
	v_max_f32_e32 v112, v68, v68
	v_max_f32_e32 v1, v112, v1
	v_max_f32_e32 v112, v93, v93
	v_max_f32_e32 v113, v92, v92
	v_max_f32_e32 v112, v113, v112
	v_max3_f32 v1, v66, v67, v1
	v_max3_f32 v112, v90, v91, v112
	v_max3_f32 v1, v1, s41, v112
	v_max_f32_e32 v112, v85, v85
	v_max_f32_e32 v113, v84, v84
	v_max_f32_e32 v112, v113, v112
	v_max_f32_e32 v113, v97, v97
	v_max_f32_e32 v114, v96, v96
	v_max_f32_e32 v113, v114, v113
	v_max3_f32 v112, v82, v83, v112
	v_max3_f32 v113, v94, v95, v113
	v_max3_f32 v1, v1, v112, v113
	ds_bpermute_b32 v112, v135, v1
	s_waitcnt lgkmcnt(0)
	v_max_f32_e32 v112, v112, v112
	v_max_f32_e32 v1, v1, v112
	ds_bpermute_b32 v112, v101, v1
	s_waitcnt lgkmcnt(0)
	v_max3_f32 v1, v111, v1, v112
	v_sub_f32_e32 v66, v66, v1
	v_sub_f32_e32 v112, v111, v1
	v_exp_f32_e32 v111, v66
	v_sub_f32_e32 v66, v67, v1
	v_exp_f32_e32 v113, v66
	v_sub_f32_e32 v66, v68, v1
	v_exp_f32_e32 v115, v66
	v_sub_f32_e32 v66, v69, v1
	v_exp_f32_e32 v117, v66
	v_sub_f32_e32 v66, v90, v1
	v_exp_f32_e32 v119, v66
	v_sub_f32_e32 v66, v91, v1
	v_exp_f32_e32 v91, v66
	v_sub_f32_e32 v66, v92, v1
	v_exp_f32_e32 v121, v66
	v_sub_f32_e32 v66, v93, v1
	v_exp_f32_e32 v93, v66
	v_sub_f32_e32 v66, v82, v1
	v_exp_f32_e32 v123, v66
	v_sub_f32_e32 v66, v83, v1
	v_exp_f32_e32 v125, v66
	v_sub_f32_e32 v66, v84, v1
	v_exp_f32_e32 v127, v66
	v_sub_f32_e32 v66, v85, v1
	v_max_f32_e32 v90, v89, v89
	v_max_f32_e32 v92, v88, v88
	v_exp_f32_e32 v129, v66
	v_sub_f32_e32 v66, v94, v1
	v_max_f32_e32 v90, v92, v90
	v_max_f32_e32 v92, v77, v77
	v_max_f32_e32 v94, v76, v76
	v_max_f32_e32 v92, v94, v92
	v_max3_f32 v90, v86, v87, v90
	v_max3_f32 v92, v74, v75, v92
	v_exp_f32_e32 v131, v66
	v_sub_f32_e32 v66, v95, v1
	v_max3_f32 v90, v90, s41, v92
	v_max_f32_e32 v92, v73, v73
	v_max_f32_e32 v94, v72, v72
	v_exp_f32_e32 v95, v66
	v_sub_f32_e32 v66, v96, v1
	v_max_f32_e32 v92, v94, v92
	v_max_f32_e32 v94, v81, v81
	v_max_f32_e32 v96, v80, v80
	v_max_f32_e32 v94, v96, v94
	v_max3_f32 v92, v70, v71, v92
	v_max3_f32 v94, v78, v79, v94
	v_max3_f32 v90, v90, v92, v94
	ds_bpermute_b32 v92, v135, v90
	v_exp_f32_e32 v152, v112
	v_exp_f32_e32 v133, v66
	v_sub_f32_e32 v66, v97, v1
	v_exp_f32_e32 v97, v66
	s_waitcnt lgkmcnt(0)
	v_max_f32_e32 v92, v92, v92
	v_max_f32_e32 v90, v90, v92
	ds_bpermute_b32 v92, v101, v90
	v_pk_mul_f32 v[84:85], v[52:53], v[152:153] op_sel_hi:[1,0]
	v_pk_mul_f32 v[82:83], v[50:51], v[152:153] op_sel_hi:[1,0]
	v_pk_mul_f32 v[68:69], v[56:57], v[152:153] op_sel_hi:[1,0]
	v_pk_mul_f32 v[66:67], v[54:55], v[152:153] op_sel_hi:[1,0]
	s_waitcnt lgkmcnt(0)
	v_max3_f32 v134, v110, v90, v92
	v_sub_f32_e32 v86, v86, v134
	v_sub_f32_e32 v151, v110, v134
	v_exp_f32_e32 v110, v86
	v_sub_f32_e32 v86, v87, v134
	v_exp_f32_e32 v112, v86
	v_sub_f32_e32 v86, v88, v134
	v_sub_f32_e32 v74, v74, v134
	v_exp_f32_e32 v114, v86
	v_sub_f32_e32 v86, v89, v134
	v_exp_f32_e32 v118, v74
	v_sub_f32_e32 v74, v75, v134
	v_exp_f32_e32 v116, v86
	v_exp_f32_e32 v90, v74
	v_sub_f32_e32 v74, v76, v134
	v_sub_f32_e32 v70, v70, v134
	v_exp_f32_e32 v120, v74
	v_pk_add_f32 v[74:75], v[110:111], 0 op_sel_hi:[1,0]
	v_exp_f32_e32 v122, v70
	v_sub_f32_e32 v70, v71, v134
	v_pk_add_f32 v[74:75], v[112:113], v[74:75]
	v_exp_f32_e32 v124, v70
	v_sub_f32_e32 v70, v72, v134
	v_pk_add_f32 v[74:75], v[114:115], v[74:75]
	v_sub_f32_e32 v76, v77, v134
	v_exp_f32_e32 v126, v70
	v_sub_f32_e32 v70, v73, v134
	v_pk_add_f32 v[74:75], v[116:117], v[74:75]
	v_exp_f32_e32 v92, v76
	v_exp_f32_e32 v128, v70
	v_sub_f32_e32 v70, v78, v134
	v_pk_add_f32 v[74:75], v[118:119], v[74:75]
	v_exp_f32_e32 v130, v70
	v_sub_f32_e32 v70, v79, v134
	v_pk_add_f32 v[74:75], v[90:91], v[74:75]
	v_exp_f32_e32 v94, v70
	v_sub_f32_e32 v70, v80, v134
	v_pk_add_f32 v[74:75], v[120:121], v[74:75]
	v_exp_f32_e32 v132, v70
	v_sub_f32_e32 v70, v81, v134
	v_exp_f32_e32 v96, v70
	v_pk_add_f32 v[70:71], v[92:93], v[74:75]
	v_exp_f32_e32 v78, v151
	v_pk_add_f32 v[70:71], v[122:123], v[70:71]
	v_mov_b32_e32 v79, v152
	v_pk_add_f32 v[70:71], v[124:125], v[70:71]
	v_add_u32_e32 v86, v150, v144
	v_pk_add_f32 v[70:71], v[126:127], v[70:71]
	v_pk_mul_f32 v[76:77], v[36:37], v[78:79] op_sel_hi:[1,0]
	v_pk_add_f32 v[70:71], v[128:129], v[70:71]
	v_pk_mul_f32 v[74:75], v[34:35], v[78:79] op_sel_hi:[1,0]
	v_pk_add_f32 v[70:71], v[130:131], v[70:71]
	v_pk_mul_f32 v[72:73], v[40:41], v[78:79] op_sel_hi:[1,0]
	v_pk_add_f32 v[70:71], v[94:95], v[70:71]
	v_pk_mul_f32 v[44:45], v[44:45], v[78:79] op_sel_hi:[1,0]
	v_pk_add_f32 v[70:71], v[132:133], v[70:71]
	v_pk_mul_f32 v[42:43], v[42:43], v[78:79] op_sel_hi:[1,0]
	v_pk_add_f32 v[70:71], v[96:97], v[70:71]
	v_pk_mul_f32 v[36:37], v[48:49], v[78:79] op_sel_hi:[1,0]
	v_pk_fma_f32 v[104:105], v[104:105], v[78:79], v[70:71]
	v_pk_mul_f32 v[70:71], v[38:39], v[78:79] op_sel_hi:[1,0]
	v_pk_mul_f32 v[34:35], v[46:47], v[78:79] op_sel_hi:[1,0]
	v_add_u32_e32 v186, v150, v144
	ds_read_b128 v[154:157], v186 offset:33280
	ds_read_b128 v[158:161], v186 offset:35328
	ds_read_b128 v[162:165], v186 offset:37376
	ds_read_b128 v[166:169], v186 offset:39424
	v_add_u32_e32 v187, v150, v146
	ds_read_b128 v[170:173], v187 offset:35328
	ds_read_b128 v[174:177], v187 offset:33280
	ds_read_b128 v[178:181], v187 offset:37376
	ds_read_b128 v[182:185], v187 offset:39424
	v_cvt_pk_bf16_f32 v54, v111, v113
	v_cvt_pk_bf16_f32 v55, v115, v117
	v_cvt_pk_bf16_f32 v56, v119, v91
	v_cvt_pk_bf16_f32 v57, v121, v93
	v_cvt_pk_bf16_f32 v38, v110, v112
	v_cvt_pk_bf16_f32 v39, v114, v116
	v_cvt_pk_bf16_f32 v40, v118, v90
	v_cvt_pk_bf16_f32 v41, v120, v92
	v_pk_mul_f32 v[60:61], v[60:61], v[152:153] op_sel_hi:[1,0]
	s_waitcnt lgkmcnt(7)
	v_mfma_f32_16x16x32_bf16 v[82:85], v[154:157], v[54:57], v[82:85]
	v_mul_f32_e64 v58, v58, v152
	v_mul_f32_e64 v59, v59, v152
	v_pk_mul_f32 v[52:53], v[64:65], v[152:153] op_sel_hi:[1,0]
	v_pk_mul_f32 v[50:51], v[62:63], v[152:153] op_sel_hi:[1,0]
	v_mfma_f32_16x16x32_bf16 v[74:77], v[154:157], v[38:41], v[74:77]
	v_add_u32_e32 v90, v150, v146
	v_cvt_pk_bf16_f32 v62, v123, v125
	s_waitcnt lgkmcnt(6)
	v_mfma_f32_16x16x32_bf16 v[66:69], v[158:161], v[54:57], v[66:69]
	v_cvt_pk_bf16_f32 v63, v127, v129
	v_cvt_pk_bf16_f32 v64, v131, v95
	v_cvt_pk_bf16_f32 v65, v133, v97
	v_mfma_f32_16x16x32_bf16 v[70:73], v[158:161], v[38:41], v[70:73]
	v_cvt_pk_bf16_f32 v46, v122, v124
	v_cvt_pk_bf16_f32 v47, v126, v128
	s_waitcnt lgkmcnt(5)
	v_mfma_f32_16x16x32_bf16 v[58:61], v[162:165], v[54:57], v[58:61]
	v_cvt_pk_bf16_f32 v48, v130, v94
	v_cvt_pk_bf16_f32 v49, v132, v96
	v_mov_b32_e32 v110, v134
	v_mfma_f32_16x16x32_bf16 v[42:45], v[162:165], v[38:41], v[42:45]
	v_mov_b32_e32 v111, v1
	s_waitcnt lgkmcnt(4)
	v_mfma_f32_16x16x32_bf16 v[86:89], v[166:169], v[54:57], v[50:53]
	v_mfma_f32_16x16x32_bf16 v[78:81], v[166:169], v[38:41], v[34:37]
	s_waitcnt lgkmcnt(3)
	v_mfma_f32_16x16x32_bf16 v[54:57], v[170:173], v[62:65], v[66:69]
	s_waitcnt lgkmcnt(1)
	v_mfma_f32_16x16x32_bf16 v[58:61], v[178:181], v[62:65], v[58:61]
	v_mfma_f32_16x16x32_bf16 v[42:45], v[178:181], v[46:49], v[42:45]
	v_mfma_f32_16x16x32_bf16 v[50:53], v[174:177], v[62:65], v[82:85]
	v_mfma_f32_16x16x32_bf16 v[34:37], v[174:177], v[46:49], v[74:77]
	v_mfma_f32_16x16x32_bf16 v[38:41], v[170:173], v[46:49], v[70:73]
	s_waitcnt lgkmcnt(0)
	v_mfma_f32_16x16x32_bf16 v[62:65], v[182:185], v[62:65], v[86:89]
	v_mfma_f32_16x16x32_bf16 v[46:49], v[182:185], v[46:49], v[78:81]

.LBB0_208:
	s_add_i32 s8, s65, 0xffffff81
	v_cmp_le_i32_e32 vcc, s8, v141
	s_and_b64 s[82:83], s[12:13], vcc
	s_and_saveexec_b64 s[80:81], s[82:83]
	s_cbranch_execz .LBB0_212
	v_add_u32_e32 v1, v145, v143
	ds_read_b128 v[66:69], v142
	ds_read_b128 v[70:73], v142 offset:64
	ds_read_b128 v[74:77], v142 offset:128
	ds_read_b128 v[78:81], v142 offset:192
	v_add_u32_e32 v186, v145, v143
	ds_read_b128 v[154:157], v186 offset:8704
	ds_read_b128 v[158:161], v186 offset:10752
	ds_read_b128 v[162:165], v186 offset:12800
	ds_read_b128 v[166:169], v186 offset:14848
	v_add_u32_e32 v187, v147, v143
	ds_read_b128 v[170:173], v187 offset:8704
	ds_read_b128 v[174:177], v187 offset:10752
	ds_read_b128 v[178:181], v187 offset:12800
	ds_read_b128 v[182:185], v187 offset:14848
	v_cmp_gt_i32_e32 vcc, s8, v151
	s_waitcnt lgkmcnt(7)
	v_mfma_f32_16x16x32_bf16 v[86:89], v[154:157], v[30:33], v[66:69]
	s_nop 0
	v_mfma_f32_16x16x32_bf16 v[66:69], v[154:157], v[26:29], v[66:69]
	s_waitcnt lgkmcnt(6)
	v_mfma_f32_16x16x32_bf16 v[90:93], v[158:161], v[30:33], v[70:73]
	v_mfma_f32_16x16x32_bf16 v[70:73], v[158:161], v[26:29], v[70:73]
	s_waitcnt lgkmcnt(5)
	v_mfma_f32_16x16x32_bf16 v[94:97], v[162:165], v[30:33], v[74:77]
	v_mfma_f32_16x16x32_bf16 v[112:115], v[162:165], v[26:29], v[74:77]
	v_add_u32_e32 v1, v147, v143
	s_waitcnt lgkmcnt(4)
	v_mfma_f32_16x16x32_bf16 v[116:119], v[166:169], v[30:33], v[78:81]
	v_mfma_f32_16x16x32_bf16 v[120:123], v[166:169], v[26:29], v[78:81]
	s_waitcnt lgkmcnt(3)
	v_mfma_f32_16x16x32_bf16 v[82:85], v[170:173], v[18:21], v[66:69]
	v_mfma_f32_16x16x32_bf16 v[74:77], v[170:173], v[22:25], v[86:89]
	s_waitcnt lgkmcnt(2)
	v_mfma_f32_16x16x32_bf16 v[90:93], v[174:177], v[22:25], v[90:93]
	v_mfma_f32_16x16x32_bf16 v[86:89], v[174:177], v[18:21], v[70:73]
	s_waitcnt lgkmcnt(1)
	v_mfma_f32_16x16x32_bf16 v[78:81], v[178:181], v[22:25], v[94:97]
	v_mfma_f32_16x16x32_bf16 v[66:69], v[178:181], v[18:21], v[112:115]
	s_waitcnt lgkmcnt(0)
	v_mfma_f32_16x16x32_bf16 v[94:97], v[182:185], v[22:25], v[116:119]
	v_mfma_f32_16x16x32_bf16 v[70:73], v[182:185], v[18:21], v[120:123]
	s_and_saveexec_b64 s[82:83], vcc
	s_cbranch_execz .LBB0_211
	v_add_u32_e32 v1, s65, v137
	v_add_u32_e32 v113, 0xffffff81, v1
	v_mov_b32_e32 v112, s41
	v_cmp_gt_i32_e32 vcc, v113, v148
	v_cmp_lt_i32_e64 s[8:9], v113, v148
	v_add_u32_e32 v114, 0xffffff83, v1
	v_cndmask_b32_e32 v112, v74, v112, vcc
	v_cndmask_b32_e64 v74, v112, v74, s[8:9]
	v_cndmask_b32_e64 v75, v221, v75, s[8:9]
	v_cmp_le_i32_e64 s[8:9], v114, v148
	v_add_u32_e32 v115, 0xffffff84, v1
	v_mov_b32_e32 v112, s41
	v_cndmask_b32_e64 v76, v221, v76, s[8:9]
	v_cmp_le_i32_e64 s[8:9], v115, v148
	v_add_u32_e32 v116, 0xffffffa4, v1
	s_nop 0
	v_cndmask_b32_e64 v77, v221, v77, s[8:9]
	v_cmp_gt_i32_e64 s[8:9], v113, v149
	s_nop 1
	v_cndmask_b32_e64 v112, v82, v112, s[8:9]
	v_cmp_lt_i32_e64 s[8:9], v113, v149
	v_add_u32_e32 v113, 0xffffff91, v1
	s_nop 0
	v_cndmask_b32_e64 v82, v112, v82, s[8:9]
	v_cndmask_b32_e64 v83, v221, v83, s[8:9]
	v_cmp_le_i32_e64 s[8:9], v114, v149
	v_mov_b32_e32 v112, s41
	v_add_u32_e32 v114, 0xffffff93, v1
	v_cndmask_b32_e64 v84, v221, v84, s[8:9]
	v_cmp_le_i32_e64 s[8:9], v115, v149
	v_cndmask_b32_e32 v86, v86, v112, vcc
	v_add_u32_e32 v115, 0xffffff94, v1
	v_cndmask_b32_e64 v85, v221, v85, s[8:9]
	v_cmp_gt_i32_e64 s[8:9], v113, v148
	v_add_u32_e32 v113, 0xffffff92, v1
	v_cmp_le_i32_e32 vcc, v113, v149
	v_cndmask_b32_e64 v90, v90, v112, s[8:9]
	v_cmp_le_i32_e64 s[8:9], v113, v148
	v_cndmask_b32_e32 v87, v221, v87, vcc
	v_cmp_le_i32_e32 vcc, v114, v149
	v_add_u32_e32 v113, 0xffffffa1, v1
	v_cndmask_b32_e64 v91, v221, v91, s[8:9]
	v_cndmask_b32_e32 v88, v221, v88, vcc
	v_cmp_le_i32_e32 vcc, v115, v149
	v_cmp_le_i32_e64 s[8:9], v114, v148
	v_add_u32_e32 v114, 0xffffffa2, v1
	v_cndmask_b32_e32 v89, v221, v89, vcc
	v_cmp_gt_i32_e32 vcc, v113, v148
	v_cndmask_b32_e64 v92, v221, v92, s[8:9]
	v_cmp_le_i32_e64 s[8:9], v115, v148
	v_cndmask_b32_e32 v78, v78, v112, vcc
	v_cmp_le_i32_e32 vcc, v114, v148
	v_add_u32_e32 v115, 0xffffffa3, v1
	v_cndmask_b32_e64 v93, v221, v93, s[8:9]
	v_cndmask_b32_e32 v79, v221, v79, vcc
	v_cmp_le_i32_e32 vcc, v115, v148
	s_nop 1
	v_cndmask_b32_e32 v80, v221, v80, vcc
	v_cmp_le_i32_e32 vcc, v116, v148
	s_nop 1
	v_cndmask_b32_e32 v81, v221, v81, vcc
	v_cmp_gt_i32_e32 vcc, v113, v149
	v_add_u32_e32 v113, 0xffffffb1, v1
	s_nop 0
	v_cndmask_b32_e32 v66, v66, v112, vcc
	v_cmp_le_i32_e32 vcc, v114, v149
	v_add_u32_e32 v114, 0xffffffb2, v1
	s_nop 0
	v_cndmask_b32_e32 v67, v221, v67, vcc
	v_cmp_le_i32_e32 vcc, v115, v149
	v_add_u32_e32 v115, 0xffffffb3, v1
	v_add_u32_e32 v1, 0xffffffb4, v1
	v_cndmask_b32_e32 v68, v221, v68, vcc
	v_cmp_le_i32_e32 vcc, v116, v149
	s_nop 1
	v_cndmask_b32_e32 v69, v221, v69, vcc
	v_cmp_gt_i32_e32 vcc, v113, v148
	s_nop 1
	v_cndmask_b32_e32 v94, v94, v112, vcc
	v_cmp_le_i32_e32 vcc, v114, v148
	s_nop 1
	v_cndmask_b32_e32 v95, v221, v95, vcc
	v_cmp_le_i32_e32 vcc, v115, v148
	s_nop 1
	v_cndmask_b32_e32 v96, v221, v96, vcc
	v_cmp_le_i32_e32 vcc, v1, v148
	s_nop 1
	v_cndmask_b32_e32 v97, v221, v97, vcc
	v_cmp_gt_i32_e32 vcc, v113, v149
	s_nop 1
	v_cndmask_b32_e32 v70, v70, v112, vcc
	v_cmp_le_i32_e32 vcc, v114, v149
	s_nop 1
	v_cndmask_b32_e32 v71, v221, v71, vcc
	v_cmp_le_i32_e32 vcc, v115, v149
	s_nop 1
	v_cndmask_b32_e32 v72, v221, v72, vcc
	v_cmp_le_i32_e32 vcc, v1, v149
	s_nop 1
	v_cndmask_b32_e32 v73, v221, v73, vcc
.LBB0_211:
	s_or_b64 exec, exec, s[82:83]
	v_max_f32_e32 v1, v77, v77
	v_max_f32_e32 v112, v76, v76
	v_max_f32_e32 v1, v112, v1
	v_max_f32_e32 v112, v93, v93
	v_max_f32_e32 v113, v92, v92
	v_max_f32_e32 v112, v113, v112
	v_max3_f32 v1, v74, v75, v1
	v_max3_f32 v112, v90, v91, v112
	v_max3_f32 v1, v1, s41, v112
	v_max_f32_e32 v112, v81, v81
	v_max_f32_e32 v113, v80, v80
	v_max_f32_e32 v112, v113, v112
	v_max_f32_e32 v113, v97, v97
	v_max_f32_e32 v114, v96, v96
	v_max_f32_e32 v113, v114, v113
	v_max3_f32 v112, v78, v79, v112
	v_max3_f32 v113, v94, v95, v113
	v_max3_f32 v1, v1, v112, v113
	ds_bpermute_b32 v112, v135, v1
	s_waitcnt lgkmcnt(0)
	v_max_f32_e32 v112, v112, v112
	v_max_f32_e32 v1, v1, v112
	ds_bpermute_b32 v112, v101, v1
	s_waitcnt lgkmcnt(0)
	v_max3_f32 v1, v111, v1, v112
	v_sub_f32_e32 v74, v74, v1
	v_sub_f32_e32 v112, v111, v1
	v_exp_f32_e32 v111, v74
	v_sub_f32_e32 v74, v75, v1
	v_exp_f32_e32 v113, v74
	v_sub_f32_e32 v74, v76, v1
	v_exp_f32_e32 v115, v74
	v_sub_f32_e32 v74, v77, v1
	v_exp_f32_e32 v117, v74
	v_sub_f32_e32 v74, v90, v1
	v_exp_f32_e32 v119, v74
	v_sub_f32_e32 v74, v91, v1
	v_exp_f32_e32 v91, v74
	v_sub_f32_e32 v74, v92, v1
	v_exp_f32_e32 v121, v74
	v_sub_f32_e32 v74, v93, v1
	v_exp_f32_e32 v93, v74
	v_sub_f32_e32 v74, v78, v1
	v_exp_f32_e32 v123, v74
	v_sub_f32_e32 v74, v79, v1
	v_exp_f32_e32 v125, v74
	v_sub_f32_e32 v74, v80, v1
	v_exp_f32_e32 v127, v74
	v_sub_f32_e32 v74, v81, v1
	v_max_f32_e32 v90, v85, v85
	v_max_f32_e32 v92, v84, v84
	v_exp_f32_e32 v129, v74
	v_sub_f32_e32 v74, v94, v1
	v_max_f32_e32 v90, v92, v90
	v_max_f32_e32 v92, v89, v89
	v_max_f32_e32 v94, v88, v88
	v_max_f32_e32 v92, v94, v92
	v_max3_f32 v90, v82, v83, v90
	v_max3_f32 v92, v86, v87, v92
	v_exp_f32_e32 v131, v74
	v_sub_f32_e32 v74, v95, v1
	v_max3_f32 v90, v90, s41, v92
	v_max_f32_e32 v92, v69, v69
	v_max_f32_e32 v94, v68, v68
	v_exp_f32_e32 v95, v74
	v_sub_f32_e32 v74, v96, v1
	v_max_f32_e32 v92, v94, v92
	v_max_f32_e32 v94, v73, v73
	v_max_f32_e32 v96, v72, v72
	v_max_f32_e32 v94, v96, v94
	v_max3_f32 v92, v66, v67, v92
	v_max3_f32 v94, v70, v71, v94
	v_max3_f32 v90, v90, v92, v94
	ds_bpermute_b32 v92, v135, v90
	v_exp_f32_e32 v134, v112
	v_exp_f32_e32 v133, v74
	v_sub_f32_e32 v74, v97, v1
	v_exp_f32_e32 v97, v74
	s_waitcnt lgkmcnt(0)
	v_max_f32_e32 v92, v92, v92
	v_max_f32_e32 v90, v90, v92
	ds_bpermute_b32 v92, v101, v90
	v_pk_mul_f32 v[80:81], v[52:53], v[134:135] op_sel_hi:[1,0]
	v_pk_mul_f32 v[78:79], v[50:51], v[134:135] op_sel_hi:[1,0]
	v_pk_mul_f32 v[76:77], v[56:57], v[134:135] op_sel_hi:[1,0]
	v_pk_mul_f32 v[74:75], v[54:55], v[134:135] op_sel_hi:[1,0]
	s_waitcnt lgkmcnt(0)
	v_max3_f32 v152, v110, v90, v92
	v_sub_f32_e32 v82, v82, v152
	v_sub_f32_e32 v153, v110, v152
	v_exp_f32_e32 v110, v82
	v_sub_f32_e32 v82, v83, v152
	v_exp_f32_e32 v112, v82
	v_sub_f32_e32 v82, v84, v152
	v_exp_f32_e32 v114, v82
	v_sub_f32_e32 v82, v85, v152
	v_sub_f32_e32 v66, v66, v152
	v_exp_f32_e32 v116, v82
	v_sub_f32_e32 v82, v86, v152
	v_exp_f32_e32 v122, v66
	v_sub_f32_e32 v66, v67, v152
	v_exp_f32_e32 v118, v82
	v_sub_f32_e32 v82, v87, v152
	v_exp_f32_e32 v124, v66
	v_pk_add_f32 v[66:67], v[110:111], 0 op_sel_hi:[1,0]
	v_exp_f32_e32 v90, v82
	v_sub_f32_e32 v82, v88, v152
	v_pk_add_f32 v[66:67], v[112:113], v[66:67]
	v_exp_f32_e32 v120, v82
	v_sub_f32_e32 v82, v89, v152
	v_pk_add_f32 v[66:67], v[114:115], v[66:67]
	v_exp_f32_e32 v92, v82
	v_pk_add_f32 v[66:67], v[116:117], v[66:67]
	v_sub_f32_e32 v68, v68, v152
	v_pk_add_f32 v[66:67], v[118:119], v[66:67]
	v_exp_f32_e32 v126, v68
	v_pk_add_f32 v[66:67], v[90:91], v[66:67]
	v_sub_f32_e32 v68, v69, v152
	v_pk_add_f32 v[66:67], v[120:121], v[66:67]
	v_exp_f32_e32 v128, v68
	v_pk_add_f32 v[66:67], v[92:93], v[66:67]
	v_sub_f32_e32 v68, v70, v152
	v_pk_add_f32 v[66:67], v[122:123], v[66:67]
	v_exp_f32_e32 v130, v68
	v_sub_f32_e32 v68, v71, v152
	v_pk_add_f32 v[66:67], v[124:125], v[66:67]
	v_exp_f32_e32 v94, v68
	v_sub_f32_e32 v68, v72, v152
	v_exp_f32_e32 v132, v68
	v_sub_f32_e32 v68, v73, v152
	v_pk_add_f32 v[66:67], v[126:127], v[66:67]
	v_exp_f32_e32 v96, v68
	v_pk_add_f32 v[66:67], v[128:129], v[66:67]
	v_exp_f32_e32 v82, v153
	v_pk_add_f32 v[66:67], v[130:131], v[66:67]
	v_mov_b32_e32 v83, v134
	v_pk_add_f32 v[66:67], v[94:95], v[66:67]
	v_add_u32_e32 v86, v150, v144
	v_pk_add_f32 v[66:67], v[132:133], v[66:67]
	v_pk_mul_f32 v[68:69], v[36:37], v[82:83] op_sel_hi:[1,0]
	v_pk_add_f32 v[66:67], v[96:97], v[66:67]
	v_pk_mul_f32 v[72:73], v[40:41], v[82:83] op_sel_hi:[1,0]
	v_pk_fma_f32 v[104:105], v[104:105], v[82:83], v[66:67]
	v_pk_mul_f32 v[66:67], v[34:35], v[82:83] op_sel_hi:[1,0]
	v_pk_mul_f32 v[70:71], v[38:39], v[82:83] op_sel_hi:[1,0]
	v_pk_mul_f32 v[44:45], v[44:45], v[82:83] op_sel_hi:[1,0]
	v_pk_mul_f32 v[42:43], v[42:43], v[82:83] op_sel_hi:[1,0]
	v_pk_mul_f32 v[36:37], v[48:49], v[82:83] op_sel_hi:[1,0]
	v_pk_mul_f32 v[34:35], v[46:47], v[82:83] op_sel_hi:[1,0]
	v_add_u32_e32 v186, v150, v144
	ds_read_b128 v[154:157], v186 offset:25088
	ds_read_b128 v[158:161], v186 offset:27136
	ds_read_b128 v[162:165], v186 offset:29184
	ds_read_b128 v[166:169], v186 offset:31232
	v_add_u32_e32 v187, v150, v146
	ds_read_b128 v[170:173], v187 offset:27136
	ds_read_b128 v[174:177], v187 offset:25088
	ds_read_b128 v[178:181], v187 offset:29184
	ds_read_b128 v[182:185], v187 offset:31232
	v_cvt_pk_bf16_f32 v54, v111, v113
	v_cvt_pk_bf16_f32 v55, v115, v117
	v_cvt_pk_bf16_f32 v56, v119, v91
	v_cvt_pk_bf16_f32 v57, v121, v93
	v_cvt_pk_bf16_f32 v38, v110, v112
	v_cvt_pk_bf16_f32 v39, v114, v116
	v_cvt_pk_bf16_f32 v40, v118, v90
	v_cvt_pk_bf16_f32 v41, v120, v92
	v_pk_mul_f32 v[60:61], v[60:61], v[134:135] op_sel_hi:[1,0]
	s_waitcnt lgkmcnt(7)
	v_mfma_f32_16x16x32_bf16 v[78:81], v[154:157], v[54:57], v[78:81]
	v_mul_f32_e64 v58, v58, v134
	v_mul_f32_e64 v59, v59, v134
	v_pk_mul_f32 v[52:53], v[64:65], v[134:135] op_sel_hi:[1,0]
	v_pk_mul_f32 v[50:51], v[62:63], v[134:135] op_sel_hi:[1,0]
	v_mfma_f32_16x16x32_bf16 v[66:69], v[154:157], v[38:41], v[66:69]
	v_add_u32_e32 v90, v150, v146
	v_cvt_pk_bf16_f32 v62, v123, v125
	s_waitcnt lgkmcnt(6)
	v_mfma_f32_16x16x32_bf16 v[74:77], v[158:161], v[54:57], v[74:77]
	v_cvt_pk_bf16_f32 v63, v127, v129
	v_cvt_pk_bf16_f32 v64, v131, v95
	v_cvt_pk_bf16_f32 v65, v133, v97
	v_mfma_f32_16x16x32_bf16 v[70:73], v[158:161], v[38:41], v[70:73]
	v_cvt_pk_bf16_f32 v46, v122, v124
	v_cvt_pk_bf16_f32 v47, v126, v128
	s_waitcnt lgkmcnt(5)
	v_mfma_f32_16x16x32_bf16 v[58:61], v[162:165], v[54:57], v[58:61]
	v_cvt_pk_bf16_f32 v48, v130, v94
	v_cvt_pk_bf16_f32 v49, v132, v96
	v_mov_b32_e32 v110, v152
	v_mfma_f32_16x16x32_bf16 v[42:45], v[162:165], v[38:41], v[42:45]
	v_mov_b32_e32 v111, v1
	s_waitcnt lgkmcnt(4)
	v_mfma_f32_16x16x32_bf16 v[86:89], v[166:169], v[54:57], v[50:53]
	v_mfma_f32_16x16x32_bf16 v[82:85], v[166:169], v[38:41], v[34:37]
	s_waitcnt lgkmcnt(2)
	v_mfma_f32_16x16x32_bf16 v[50:53], v[174:177], v[62:65], v[78:81]
	v_mfma_f32_16x16x32_bf16 v[34:37], v[174:177], v[46:49], v[66:69]
	s_waitcnt lgkmcnt(1)
	v_mfma_f32_16x16x32_bf16 v[58:61], v[178:181], v[62:65], v[58:61]
	v_mfma_f32_16x16x32_bf16 v[42:45], v[178:181], v[46:49], v[42:45]
	v_mfma_f32_16x16x32_bf16 v[54:57], v[170:173], v[62:65], v[74:77]
	v_mfma_f32_16x16x32_bf16 v[38:41], v[170:173], v[46:49], v[70:73]
	s_waitcnt lgkmcnt(0)
	v_mfma_f32_16x16x32_bf16 v[62:65], v[182:185], v[62:65], v[86:89]
	v_mfma_f32_16x16x32_bf16 v[46:49], v[182:185], v[46:49], v[82:85]

.LBB0_217:
	s_sub_i32 s8, s65, 63
	v_cmp_le_i32_e32 vcc, s8, v141
	s_and_b64 s[8:9], s[12:13], vcc
	s_and_saveexec_b64 s[80:81], s[8:9]
	s_cbranch_execz .LBB0_221
	v_add_u32_e32 v1, v145, v143
	ds_read_b128 v[66:69], v142 offset:256
	ds_read_b128 v[70:73], v142 offset:320
	ds_read_b128 v[74:77], v142 offset:384
	ds_read_b128 v[78:81], v142 offset:448
	v_add_u32_e32 v186, v145, v143
	ds_read_b128 v[154:157], v186 offset:16896
	ds_read_b128 v[158:161], v186 offset:18944
	ds_read_b128 v[162:165], v186 offset:20992
	ds_read_b128 v[166:169], v186 offset:23040
	v_add_u32_e32 v187, v147, v143
	ds_read_b128 v[170:173], v187 offset:16896
	ds_read_b128 v[174:177], v187 offset:18944
	ds_read_b128 v[178:181], v187 offset:20992
	ds_read_b128 v[182:185], v187 offset:23040
	v_cmp_gt_u32_e32 vcc, s65, v136
	s_waitcnt lgkmcnt(7)
	v_mfma_f32_16x16x32_bf16 v[86:89], v[154:157], v[30:33], v[66:69]
	s_nop 0
	v_mfma_f32_16x16x32_bf16 v[82:85], v[154:157], v[26:29], v[66:69]
	s_waitcnt lgkmcnt(6)
	v_mfma_f32_16x16x32_bf16 v[90:93], v[158:161], v[30:33], v[70:73]
	v_mfma_f32_16x16x32_bf16 v[70:73], v[158:161], v[26:29], v[70:73]
	s_waitcnt lgkmcnt(5)
	v_mfma_f32_16x16x32_bf16 v[94:97], v[162:165], v[30:33], v[74:77]
	v_mfma_f32_16x16x32_bf16 v[112:115], v[162:165], v[26:29], v[74:77]
	v_add_u32_e32 v1, v147, v143
	s_waitcnt lgkmcnt(4)
	v_mfma_f32_16x16x32_bf16 v[116:119], v[166:169], v[30:33], v[78:81]
	v_mfma_f32_16x16x32_bf16 v[78:81], v[166:169], v[26:29], v[78:81]
	s_waitcnt lgkmcnt(3)
	v_mfma_f32_16x16x32_bf16 v[66:69], v[170:173], v[22:25], v[86:89]
	s_nop 0
	v_mfma_f32_16x16x32_bf16 v[86:89], v[170:173], v[18:21], v[82:85]
	s_waitcnt lgkmcnt(2)
	v_mfma_f32_16x16x32_bf16 v[90:93], v[174:177], v[22:25], v[90:93]
	v_mfma_f32_16x16x32_bf16 v[74:77], v[174:177], v[18:21], v[70:73]
	s_waitcnt lgkmcnt(1)
	v_mfma_f32_16x16x32_bf16 v[82:85], v[178:181], v[22:25], v[94:97]
	v_mfma_f32_16x16x32_bf16 v[70:73], v[178:181], v[18:21], v[112:115]
	s_waitcnt lgkmcnt(0)
	v_mfma_f32_16x16x32_bf16 v[94:97], v[182:185], v[22:25], v[116:119]
	v_mfma_f32_16x16x32_bf16 v[78:81], v[182:185], v[18:21], v[78:81]
	s_and_saveexec_b64 s[82:83], vcc
	s_cbranch_execz .LBB0_220
	v_add_u32_e32 v1, s65, v137
	v_subrev_u32_e32 v113, 63, v1
	v_mov_b32_e32 v112, s41
	v_cmp_gt_i32_e32 vcc, v113, v148
	v_cmp_lt_i32_e64 s[8:9], v113, v148
	v_subrev_u32_e32 v114, 61, v1
	v_cndmask_b32_e32 v112, v66, v112, vcc
	v_cndmask_b32_e64 v66, v112, v66, s[8:9]
	v_cndmask_b32_e64 v67, v221, v67, s[8:9]
	v_cmp_le_i32_e64 s[8:9], v114, v148
	v_subrev_u32_e32 v115, 60, v1
	v_mov_b32_e32 v112, s41
	v_cndmask_b32_e64 v68, v221, v68, s[8:9]
	v_cmp_le_i32_e64 s[8:9], v115, v148
	v_subrev_u32_e32 v116, 28, v1
	s_nop 0
	v_cndmask_b32_e64 v69, v221, v69, s[8:9]
	v_cmp_gt_i32_e64 s[8:9], v113, v149
	s_nop 1
	v_cndmask_b32_e64 v112, v86, v112, s[8:9]
	v_cmp_lt_i32_e64 s[8:9], v113, v149
	v_subrev_u32_e32 v113, 47, v1
	s_nop 0
	v_cndmask_b32_e64 v86, v112, v86, s[8:9]
	v_cndmask_b32_e64 v87, v221, v87, s[8:9]
	v_cmp_le_i32_e64 s[8:9], v114, v149
	v_mov_b32_e32 v112, s41
	v_subrev_u32_e32 v114, 45, v1
	v_cndmask_b32_e64 v88, v221, v88, s[8:9]
	v_cmp_le_i32_e64 s[8:9], v115, v149
	v_cndmask_b32_e32 v74, v74, v112, vcc
	v_subrev_u32_e32 v115, 44, v1
	v_cndmask_b32_e64 v89, v221, v89, s[8:9]
	v_cmp_gt_i32_e64 s[8:9], v113, v148
	v_subrev_u32_e32 v113, 46, v1
	v_cmp_le_i32_e32 vcc, v113, v149
	v_cndmask_b32_e64 v90, v90, v112, s[8:9]
	v_cmp_le_i32_e64 s[8:9], v113, v148
	v_cndmask_b32_e32 v75, v221, v75, vcc
	v_cmp_le_i32_e32 vcc, v114, v149
	v_subrev_u32_e32 v113, 31, v1
	v_cndmask_b32_e64 v91, v221, v91, s[8:9]
	v_cndmask_b32_e32 v76, v221, v76, vcc
	v_cmp_le_i32_e32 vcc, v115, v149
	v_cmp_le_i32_e64 s[8:9], v114, v148
	v_subrev_u32_e32 v114, 30, v1
	v_cndmask_b32_e32 v77, v221, v77, vcc
	v_cmp_gt_i32_e32 vcc, v113, v148
	v_cndmask_b32_e64 v92, v221, v92, s[8:9]
	v_cmp_le_i32_e64 s[8:9], v115, v148
	v_cndmask_b32_e32 v82, v82, v112, vcc
	v_cmp_le_i32_e32 vcc, v114, v148
	v_subrev_u32_e32 v115, 29, v1
	v_cndmask_b32_e64 v93, v221, v93, s[8:9]
	v_cndmask_b32_e32 v83, v221, v83, vcc
	v_cmp_le_i32_e32 vcc, v115, v148
	s_nop 1
	v_cndmask_b32_e32 v84, v221, v84, vcc
	v_cmp_le_i32_e32 vcc, v116, v148
	s_nop 1
	v_cndmask_b32_e32 v85, v221, v85, vcc
	v_cmp_gt_i32_e32 vcc, v113, v149
	v_add_u32_e32 v113, -15, v1
	s_nop 0
	v_cndmask_b32_e32 v70, v70, v112, vcc
	v_cmp_le_i32_e32 vcc, v114, v149
	v_add_u32_e32 v114, -14, v1
	s_nop 0
	v_cndmask_b32_e32 v71, v221, v71, vcc
	v_cmp_le_i32_e32 vcc, v115, v149
	v_add_u32_e32 v115, -13, v1
	v_add_u32_e32 v1, -12, v1
	v_cndmask_b32_e32 v72, v221, v72, vcc
	v_cmp_le_i32_e32 vcc, v116, v149
	s_nop 1
	v_cndmask_b32_e32 v73, v221, v73, vcc
	v_cmp_gt_i32_e32 vcc, v113, v148
	s_nop 1
	v_cndmask_b32_e32 v94, v94, v112, vcc
	v_cmp_le_i32_e32 vcc, v114, v148
	s_nop 1
	v_cndmask_b32_e32 v95, v221, v95, vcc
	v_cmp_le_i32_e32 vcc, v115, v148
	s_nop 1
	v_cndmask_b32_e32 v96, v221, v96, vcc
	v_cmp_le_i32_e32 vcc, v1, v148
	s_nop 1
	v_cndmask_b32_e32 v97, v221, v97, vcc
	v_cmp_gt_i32_e32 vcc, v113, v149
	s_nop 1
	v_cndmask_b32_e32 v78, v78, v112, vcc
	v_cmp_le_i32_e32 vcc, v114, v149
	s_nop 1
	v_cndmask_b32_e32 v79, v221, v79, vcc
	v_cmp_le_i32_e32 vcc, v115, v149
	s_nop 1
	v_cndmask_b32_e32 v80, v221, v80, vcc
	v_cmp_le_i32_e32 vcc, v1, v149
	s_nop 1
	v_cndmask_b32_e32 v81, v221, v81, vcc
.LBB0_220:
	s_or_b64 exec, exec, s[82:83]
	v_max_f32_e32 v1, v69, v69
	v_max_f32_e32 v112, v68, v68
	v_max_f32_e32 v1, v112, v1
	v_max_f32_e32 v112, v93, v93
	v_max_f32_e32 v113, v92, v92
	v_max_f32_e32 v112, v113, v112
	v_max3_f32 v1, v66, v67, v1
	v_max3_f32 v112, v90, v91, v112
	v_max3_f32 v1, v1, s41, v112
	v_max_f32_e32 v112, v85, v85
	v_max_f32_e32 v113, v84, v84
	v_max_f32_e32 v112, v113, v112
	v_max_f32_e32 v113, v97, v97
	v_max_f32_e32 v114, v96, v96
	v_max_f32_e32 v113, v114, v113
	v_max3_f32 v112, v82, v83, v112
	v_max3_f32 v113, v94, v95, v113
	v_max3_f32 v1, v1, v112, v113
	ds_bpermute_b32 v112, v135, v1
	s_waitcnt lgkmcnt(0)
	v_max_f32_e32 v112, v112, v112
	v_max_f32_e32 v1, v1, v112
	ds_bpermute_b32 v112, v101, v1
	s_waitcnt lgkmcnt(0)
	v_max3_f32 v1, v111, v1, v112
	v_sub_f32_e32 v66, v66, v1
	v_sub_f32_e32 v112, v111, v1
	v_exp_f32_e32 v111, v66
	v_sub_f32_e32 v66, v67, v1
	v_exp_f32_e32 v113, v66
	v_sub_f32_e32 v66, v68, v1
	v_exp_f32_e32 v115, v66
	v_sub_f32_e32 v66, v69, v1
	v_exp_f32_e32 v117, v66
	v_sub_f32_e32 v66, v90, v1
	v_exp_f32_e32 v119, v66
	v_sub_f32_e32 v66, v91, v1
	v_exp_f32_e32 v91, v66
	v_sub_f32_e32 v66, v92, v1
	v_exp_f32_e32 v121, v66
	v_sub_f32_e32 v66, v93, v1
	v_exp_f32_e32 v93, v66
	v_sub_f32_e32 v66, v82, v1
	v_exp_f32_e32 v123, v66
	v_sub_f32_e32 v66, v83, v1
	v_exp_f32_e32 v125, v66
	v_sub_f32_e32 v66, v84, v1
	v_exp_f32_e32 v127, v66
	v_sub_f32_e32 v66, v85, v1
	v_max_f32_e32 v90, v89, v89
	v_max_f32_e32 v92, v88, v88
	v_exp_f32_e32 v129, v66
	v_sub_f32_e32 v66, v94, v1
	v_max_f32_e32 v90, v92, v90
	v_max_f32_e32 v92, v77, v77
	v_max_f32_e32 v94, v76, v76
	v_max_f32_e32 v92, v94, v92
	v_max3_f32 v90, v86, v87, v90
	v_max3_f32 v92, v74, v75, v92
	v_exp_f32_e32 v131, v66
	v_sub_f32_e32 v66, v95, v1
	v_max3_f32 v90, v90, s41, v92
	v_max_f32_e32 v92, v73, v73
	v_max_f32_e32 v94, v72, v72
	v_exp_f32_e32 v95, v66
	v_sub_f32_e32 v66, v96, v1
	v_max_f32_e32 v92, v94, v92
	v_max_f32_e32 v94, v81, v81
	v_max_f32_e32 v96, v80, v80
	v_max_f32_e32 v94, v96, v94
	v_max3_f32 v92, v70, v71, v92
	v_max3_f32 v94, v78, v79, v94
	v_max3_f32 v90, v90, v92, v94
	ds_bpermute_b32 v92, v135, v90
	v_exp_f32_e32 v152, v112
	v_exp_f32_e32 v133, v66
	v_sub_f32_e32 v66, v97, v1
	v_exp_f32_e32 v97, v66
	s_waitcnt lgkmcnt(0)
	v_max_f32_e32 v92, v92, v92
	v_max_f32_e32 v90, v90, v92
	ds_bpermute_b32 v92, v101, v90
	v_pk_mul_f32 v[84:85], v[52:53], v[152:153] op_sel_hi:[1,0]
	v_pk_mul_f32 v[82:83], v[50:51], v[152:153] op_sel_hi:[1,0]
	v_pk_mul_f32 v[68:69], v[56:57], v[152:153] op_sel_hi:[1,0]
	v_pk_mul_f32 v[66:67], v[54:55], v[152:153] op_sel_hi:[1,0]
	s_waitcnt lgkmcnt(0)
	v_max3_f32 v134, v110, v90, v92
	v_sub_f32_e32 v86, v86, v134
	v_pk_mul_f32 v[60:61], v[60:61], v[152:153] op_sel_hi:[1,0]
	v_pk_mul_f32 v[58:59], v[58:59], v[152:153] op_sel_hi:[1,0]
	v_pk_mul_f32 v[52:53], v[64:65], v[152:153] op_sel_hi:[1,0]
	v_pk_mul_f32 v[50:51], v[62:63], v[152:153] op_sel_hi:[1,0]
	v_sub_f32_e32 v153, v110, v134
	v_exp_f32_e32 v110, v86
	v_sub_f32_e32 v86, v87, v134
	v_exp_f32_e32 v112, v86
	v_sub_f32_e32 v86, v88, v134
	v_sub_f32_e32 v74, v74, v134
	v_exp_f32_e32 v114, v86
	v_sub_f32_e32 v86, v89, v134
	v_exp_f32_e32 v118, v74
	v_sub_f32_e32 v74, v75, v134
	v_exp_f32_e32 v116, v86
	v_exp_f32_e32 v90, v74
	v_sub_f32_e32 v74, v76, v134
	v_sub_f32_e32 v70, v70, v134
	v_exp_f32_e32 v120, v74
	v_pk_add_f32 v[74:75], v[110:111], 0 op_sel_hi:[1,0]
	v_exp_f32_e32 v122, v70
	v_sub_f32_e32 v70, v71, v134
	v_pk_add_f32 v[74:75], v[112:113], v[74:75]
	v_exp_f32_e32 v124, v70
	v_sub_f32_e32 v70, v72, v134
	v_pk_add_f32 v[74:75], v[114:115], v[74:75]
	v_sub_f32_e32 v76, v77, v134
	v_exp_f32_e32 v126, v70
	v_sub_f32_e32 v70, v73, v134
	v_pk_add_f32 v[74:75], v[116:117], v[74:75]
	v_exp_f32_e32 v92, v76
	v_exp_f32_e32 v128, v70
	v_sub_f32_e32 v70, v78, v134
	v_pk_add_f32 v[74:75], v[118:119], v[74:75]
	v_exp_f32_e32 v130, v70
	v_sub_f32_e32 v70, v79, v134
	v_pk_add_f32 v[74:75], v[90:91], v[74:75]
	v_exp_f32_e32 v94, v70
	v_sub_f32_e32 v70, v80, v134
	v_pk_add_f32 v[74:75], v[120:121], v[74:75]
	v_exp_f32_e32 v132, v70
	v_sub_f32_e32 v70, v81, v134
	v_exp_f32_e32 v96, v70
	v_pk_add_f32 v[70:71], v[92:93], v[74:75]
	v_exp_f32_e32 v78, v153
	v_pk_add_f32 v[70:71], v[122:123], v[70:71]
	v_mov_b32_e32 v79, v152
	v_pk_add_f32 v[70:71], v[124:125], v[70:71]
	v_add_u32_e32 v86, v150, v144
	v_pk_add_f32 v[70:71], v[126:127], v[70:71]
	v_pk_mul_f32 v[76:77], v[36:37], v[78:79] op_sel_hi:[1,0]
	v_pk_add_f32 v[70:71], v[128:129], v[70:71]
	v_pk_mul_f32 v[74:75], v[34:35], v[78:79] op_sel_hi:[1,0]
	v_pk_add_f32 v[70:71], v[130:131], v[70:71]
	v_pk_mul_f32 v[72:73], v[40:41], v[78:79] op_sel_hi:[1,0]
	v_pk_add_f32 v[70:71], v[94:95], v[70:71]
	v_pk_mul_f32 v[44:45], v[44:45], v[78:79] op_sel_hi:[1,0]
	v_pk_add_f32 v[70:71], v[132:133], v[70:71]
	v_pk_mul_f32 v[42:43], v[42:43], v[78:79] op_sel_hi:[1,0]
	v_pk_add_f32 v[70:71], v[96:97], v[70:71]
	v_pk_mul_f32 v[36:37], v[48:49], v[78:79] op_sel_hi:[1,0]
	v_pk_fma_f32 v[104:105], v[104:105], v[78:79], v[70:71]
	v_pk_mul_f32 v[70:71], v[38:39], v[78:79] op_sel_hi:[1,0]
	v_pk_mul_f32 v[34:35], v[46:47], v[78:79] op_sel_hi:[1,0]
	v_add_u32_e32 v186, v150, v144
	ds_read_b128 v[154:157], v186 offset:33280
	ds_read_b128 v[158:161], v186 offset:35328
	ds_read_b128 v[162:165], v186 offset:37376
	ds_read_b128 v[166:169], v186 offset:39424
	v_add_u32_e32 v187, v150, v146
	ds_read_b128 v[170:173], v187 offset:35328
	ds_read_b128 v[174:177], v187 offset:33280
	ds_read_b128 v[178:181], v187 offset:37376
	ds_read_b128 v[182:185], v187 offset:39424
	v_cvt_pk_bf16_f32 v54, v111, v113
	v_cvt_pk_bf16_f32 v55, v115, v117
	v_cvt_pk_bf16_f32 v56, v119, v91
	v_cvt_pk_bf16_f32 v57, v121, v93
	v_cvt_pk_bf16_f32 v38, v110, v112
	v_cvt_pk_bf16_f32 v39, v114, v116
	v_cvt_pk_bf16_f32 v40, v118, v90
	v_cvt_pk_bf16_f32 v41, v120, v92
	v_add_u32_e32 v90, v150, v146
	s_waitcnt lgkmcnt(7)
	v_mfma_f32_16x16x32_bf16 v[82:85], v[154:157], v[54:57], v[82:85]
	v_cvt_pk_bf16_f32 v62, v123, v125
	v_cvt_pk_bf16_f32 v63, v127, v129
	v_cvt_pk_bf16_f32 v64, v131, v95
	v_mfma_f32_16x16x32_bf16 v[74:77], v[154:157], v[38:41], v[74:77]
	v_cvt_pk_bf16_f32 v65, v133, v97
	v_cvt_pk_bf16_f32 v46, v122, v124
	s_waitcnt lgkmcnt(6)
	v_mfma_f32_16x16x32_bf16 v[66:69], v[158:161], v[54:57], v[66:69]
	v_cvt_pk_bf16_f32 v47, v126, v128
	v_cvt_pk_bf16_f32 v48, v130, v94
	v_cvt_pk_bf16_f32 v49, v132, v96
	v_mfma_f32_16x16x32_bf16 v[70:73], v[158:161], v[38:41], v[70:73]
	v_mov_b32_e32 v110, v134
	v_mov_b32_e32 v111, v1
	s_waitcnt lgkmcnt(5)
	v_mfma_f32_16x16x32_bf16 v[58:61], v[162:165], v[54:57], v[58:61]
	v_mfma_f32_16x16x32_bf16 v[42:45], v[162:165], v[38:41], v[42:45]
	s_waitcnt lgkmcnt(4)
	v_mfma_f32_16x16x32_bf16 v[86:89], v[166:169], v[54:57], v[50:53]
	v_mfma_f32_16x16x32_bf16 v[78:81], v[166:169], v[38:41], v[34:37]
	s_waitcnt lgkmcnt(3)
	v_mfma_f32_16x16x32_bf16 v[54:57], v[170:173], v[62:65], v[66:69]
	s_waitcnt lgkmcnt(1)
	v_mfma_f32_16x16x32_bf16 v[58:61], v[178:181], v[62:65], v[58:61]
	v_mfma_f32_16x16x32_bf16 v[42:45], v[178:181], v[46:49], v[42:45]
	v_mfma_f32_16x16x32_bf16 v[50:53], v[174:177], v[62:65], v[82:85]
	v_mfma_f32_16x16x32_bf16 v[34:37], v[174:177], v[46:49], v[74:77]
	v_mfma_f32_16x16x32_bf16 v[38:41], v[170:173], v[46:49], v[70:73]
	s_waitcnt lgkmcnt(0)
	v_mfma_f32_16x16x32_bf16 v[62:65], v[182:185], v[62:65], v[86:89]
	v_mfma_f32_16x16x32_bf16 v[46:49], v[182:185], v[46:49], v[78:81]

.LBB0_628:
	s_cmpk_gt_i32 s52, 0x73f
	s_mov_b64 s[6:7], -1
	s_cbranch_scc0 .LBB0_658
	s_cmpk_gt_u32 s52, 0xa3f
	s_cbranch_scc0 .LBB0_655
	s_cmpk_gt_u32 s52, 0xe3f
	s_cbranch_scc0 .LBB0_636
	s_cmpk_gt_u32 s52, 0x123f
	s_cbranch_scc0 .LBB0_633
	s_load_dwordx2 s[6:7], s[0:1], 0x18
	v_and_b32_e32 v72, 63, v208
	v_lshrrev_b32_e32 v73, 6, v208
	v_lshl_add_u32 v74, v73, 10, v72
	v_lshlrev_b32_e32 v74, 2, v74
	v_add_u32_e32 v75, 0x8000, v74
	v_add_u32_e32 v76, 0x10000, v74
	v_add_u32_e32 v77, 0x18000, v74
	v_add_u32_e32 v78, 0x20000, v74
	v_add_u32_e32 v79, 0x28000, v74
	v_add_u32_e32 v80, 0x30000, v74
	v_add_u32_e32 v81, 0x38000, v74
	v_mul_u32_u24_e32 v82, 65, v73
	v_add_lshl_u32 v82, v82, v72, 2
	v_lshrrev_b32_e32 v83, 3, v208
	v_and_b32_e32 v84, 7, v208
	v_lshlrev_b32_e32 v84, 3, v84
	v_mul_u32_u24_e32 v85, 0x104, v84
	v_lshl_add_u32 v85, v83, 2, v85
	v_mul_u32_u24_e32 v86, 0x440, v83
	v_add_lshl_u32 v86, v86, v84, 1
	s_waitcnt lgkmcnt(0)
	s_add_i32 s22, s52, 0xffffedc0
	s_lshr_b32 s23, s22, 8
	s_lshl_b32 s23, s23, 22
	s_and_b32 s56, s22, 15
	s_lshl_b32 s56, s56, 18
	s_add_u32 s23, s23, s56
	s_lshr_b32 s56, s22, 4
	s_and_b32 s56, s56, 15
	s_lshl_b32 s56, s56, 8
	s_add_u32 s23, s23, s56
	s_add_u32 s10, s6, s23
	s_addc_u32 s11, s7, 0
	global_load_dword v88, v74, s[10:11]
	global_load_dword v89, v75, s[10:11]
	global_load_dword v90, v76, s[10:11]
	global_load_dword v91, v77, s[10:11]
	global_load_dword v92, v78, s[10:11]
	global_load_dword v93, v79, s[10:11]
	global_load_dword v94, v80, s[10:11]
	global_load_dword v95, v81, s[10:11]
	s_add_i32 s22, s52, 0xffffedc0
	s_lshr_b32 s23, s22, 4
	s_mul_i32 s23, s23, 0x22000
	s_and_b32 s56, s22, 15
	s_lshl_b32 s56, s56, 7
	s_add_u32 s23, s23, s56
	s_add_u32 s12, s16, s23
	s_addc_u32 s13, s17, 0
	s_mov_b32 s20, 0
	s_waitcnt vmcnt(0)
.Lp0v_loop:
	s_waitcnt vmcnt(1)
	v_add_u32_e32 v87, s20, v82
	ds_write_b32 v87, v88
	ds_write_b32 v87, v89 offset:2080
	ds_write_b32 v87, v90 offset:4160
	ds_write_b32 v87, v91 offset:6240
	ds_write_b32 v87, v92 offset:8320
	ds_write_b32 v87, v93 offset:10400
	ds_write_b32 v87, v94 offset:12480
	ds_write_b32 v87, v95 offset:14560
	s_waitcnt lgkmcnt(0)
	s_add_i32 s21, s52, s25
	s_cmpk_gt_i32 s21, 0x323f
	s_cbranch_scc1 .Lp0v_nonext
	s_add_i32 s22, s21, 0xffffedc0
	s_lshr_b32 s23, s22, 8
	s_lshl_b32 s23, s23, 22
	s_and_b32 s56, s22, 15
	s_lshl_b32 s56, s56, 18
	s_add_u32 s23, s23, s56
	s_lshr_b32 s56, s22, 4
	s_and_b32 s56, s56, 15
	s_lshl_b32 s56, s56, 8
	s_add_u32 s23, s23, s56
	s_add_u32 s10, s6, s23
	s_addc_u32 s11, s7, 0
	global_load_dword v88, v74, s[10:11]
	global_load_dword v89, v75, s[10:11]
	global_load_dword v90, v76, s[10:11]
	global_load_dword v91, v77, s[10:11]
	global_load_dword v92, v78, s[10:11]
	global_load_dword v93, v79, s[10:11]
	global_load_dword v94, v80, s[10:11]
	global_load_dword v95, v81, s[10:11]
.Lp0v_nonext:
	s_barrier
	v_add_u32_e32 v87, s20, v85
	ds_read2_b32 v[96:97], v87 offset1:65
	ds_read2_b32 v[98:99], v87 offset0:130 offset1:195
	v_add_u32_e32 v87, 0x410, v87
	ds_read2_b32 v[100:101], v87 offset1:65
	ds_read2_b32 v[102:103], v87 offset0:130 offset1:195
	s_waitcnt lgkmcnt(0)
	v_cvt_pk_bf16_f32 v104, v96, v97
	v_cvt_pk_bf16_f32 v105, v98, v99
	v_cvt_pk_bf16_f32 v106, v100, v101
	v_cvt_pk_bf16_f32 v107, v102, v103
	global_store_dwordx4 v86, v[104:107], s[12:13]
	s_xor_b32 s20, s20, 0x4200
	s_mov_b32 s52, s21
	s_add_i32 s22, s52, 0xffffedc0
	s_lshr_b32 s23, s22, 4
	s_mul_i32 s23, s23, 0x22000
	s_and_b32 s56, s22, 15
	s_lshl_b32 s56, s56, 7
	s_add_u32 s23, s23, s56
	s_add_u32 s12, s16, s23
	s_addc_u32 s13, s17, 0
	s_cmpk_gt_i32 s52, 0x323f
	s_cbranch_scc0 .Lp0v_loop
	s_branch .LBB0_681
